# 2D XCD partition (panel parity x weight-tile residue mod 4, panel-major order) for gemmG and gemm4; grouped 1D order for the others
# speedup vs baseline: 1.0150x; 1.0150x over previous
.LBB0_608:
	s_lshr_b32 s98, s3, 3
	s_and_b32 s99, s3, 7
	s_and_b32 s100, s88, 1
	s_lshl_b32 s98, s98, 1
	s_or_b32 s98, s98, s100
	s_lshr_b32 s100, s88, 1
	s_lshl_b32 s99, s99, 2
	s_or_b32 s99, s99, s100
	s_and_b32 s101, s98, 7
	s_lshr_b32 s98, s98, 3
	s_mul_i32 s99, s99, 17
	s_add_u32 s98, s98, s99
	s_lshl_b32 s99, s98, 3
	s_or_b32 s99, s99, s101
	s_mul_hi_i32 s10, s98, 0x78787879
	s_lshr_b32 s11, s10, 31
	s_ashr_i32 s10, s10, 3
	s_add_i32 s10, s10, s11
	s_mul_i32 s11, s10, 0xffffffef
	s_add_i32 s11, s11, s98
	s_lshl_b32 s11, s11, 3
	s_or_b32 s12, s11, s101
	v_mov_b32_e32 v0, v174
	s_ashr_i32 s13, s12, 31
	s_lshl_b64 s[34:35], s[12:13], 18
	v_bfe_u32 v2, v0, 1, 3
	v_lshrrev_b32_e32 v3, 4, v0
	v_bfe_u32 v4, v0, 4, 2
	v_lshlrev_b32_e32 v5, 7, v0
	v_and_b32_e32 v6, 0x780, v5
	v_bitop3_b32 v3, v3, v2, 3 bitop3:0x6c
	v_bitop3_b32 v2, v4, v2, 4 bitop3:0x36
	s_add_u32 s34, s38, s34
	v_lshl_or_b32 v7, v3, 4, v6
	v_lshl_or_b32 v6, v2, 4, v6
	v_lshlrev_b32_e32 v2, 6, v0
	s_addc_u32 s35, s39, s35
	s_ashr_i32 s11, s10, 31
	v_lshlrev_b32_e32 v1, 8, v0
	v_and_b32_e32 v8, 0xffffe000, v2
	v_lshlrev_b32_e32 v2, 4, v0
	s_lshl_b64 s[84:85], s[10:11], 18
	v_and_b32_e32 v1, 0xfffff800, v1
	v_xor_b32_e32 v0, v2, v0
	s_movk_i32 s11, 0x70
	v_add_u32_e32 v100, 0, v2
	v_and_or_b32 v64, v0, s11, v1
	v_readfirstlane_b32 s11, v100
	v_add_u32_e32 v101, 0x1000, v100
	s_mov_b32 m0, s11
	v_readfirstlane_b32 s11, v101
	v_add_u32_e32 v102, 0x2000, v100
	global_load_lds_dwordx4 v64, s[34:35]
	v_add_u32_e32 v0, 0x10000, v64
	s_mov_b32 m0, s11
	v_readfirstlane_b32 s11, v102
	v_add_u32_e32 v103, 0x3000, v100
	global_load_lds_dwordx4 v0, s[34:35]
	v_add_u32_e32 v2, 0x20000, v64
	s_mov_b32 m0, s11
	v_readfirstlane_b32 s11, v103
	v_add_u32_e32 v104, 0x4000, v100
	s_add_u32 s86, s90, s84
	global_load_lds_dwordx4 v2, s[34:35]
	v_add_u32_e32 v4, 0x30000, v64
	s_mov_b32 m0, s11
	v_readfirstlane_b32 s11, v104
	v_add_u32_e32 v105, 0x5000, v100
	s_addc_u32 s87, s91, s85
	global_load_lds_dwordx4 v4, s[34:35]
	s_mov_b32 m0, s11
	v_readfirstlane_b32 s11, v105
	v_add_u32_e32 v106, 0x6000, v100
	global_load_lds_dwordx4 v64, s[86:87]
	s_mov_b32 m0, s11
	v_readfirstlane_b32 s11, v106
	v_add_u32_e32 v107, 0x7000, v100
	global_load_lds_dwordx4 v0, s[86:87]
	s_mov_b32 m0, s11
	v_readfirstlane_b32 s11, v107
	global_load_lds_dwordx4 v2, s[86:87]
	s_mov_b32 m0, s11
	s_mul_i32 s11, s10, 0x88
	global_load_lds_dwordx4 v4, s[86:87]
	s_sub_i32 s34, s99, s11
	s_ashr_i32 s35, s34, 31
	s_lshl_b64 s[34:35], s[34:35], 18
	s_add_u32 s34, s38, s34
	v_and_b32_e32 v9, 0x2000, v5
	v_mov_b32_e32 v1, v65
	v_mov_b32_e32 v3, v65
	v_mov_b32_e32 v5, v65
	s_addc_u32 s35, s39, s35
	v_lshl_add_u64 v[66:67], s[34:35], 0, v[64:65]
	v_lshl_add_u64 v[68:69], s[34:35], 0, v[0:1]
	v_lshl_add_u64 v[70:71], s[34:35], 0, v[2:3]
	v_lshl_add_u64 v[72:73], s[34:35], 0, v[4:5]
	s_add_u32 s34, s36, s84
	v_add_u32_e32 v8, 0, v8
	v_add_u32_e32 v9, 0, v9
	s_addc_u32 s35, s37, s85
	v_lshl_add_u64 v[74:75], s[34:35], 0, v[64:65]
	v_lshl_add_u64 v[76:77], s[34:35], 0, v[0:1]
	v_lshl_add_u64 v[78:79], s[34:35], 0, v[2:3]
	v_lshl_add_u64 v[80:81], s[34:35], 0, v[4:5]
	s_mov_b64 s[84:85], 0
	v_add_u32_e32 v64, 0x8000, v100
	v_add_u32_e32 v108, 0x9000, v100
	v_add_u32_e32 v109, 0xa000, v100
	v_add_u32_e32 v110, 0xb000, v100
	v_add_u32_e32 v111, 0xc000, v100
	v_add_u32_e32 v112, 0xd000, v100
	v_add_u32_e32 v113, 0xe000, v100
	v_add_u32_e32 v114, 0xf000, v100
	v_add_u32_e32 v115, v8, v7
	v_add_u32_e32 v116, v9, v7
	v_add_u32_e32 v117, v8, v6
	v_add_u32_e32 v118, v9, v6
	s_mov_b32 s11, 0
	v_mov_b32_e32 v0, 0
	v_mov_b32_e32 v2, v65
	v_mov_b32_e32 v4, 0
	v_mov_b32_e32 v6, v65
	v_mov_b32_e32 v7, v65
	v_mov_b32_e32 v8, 0
	v_mov_b32_e32 v9, v65
	v_mov_b32_e32 v10, v65
	v_mov_b32_e32 v11, v65
	v_mov_b32_e32 v12, 0
	v_mov_b32_e32 v13, v65
	v_mov_b32_e32 v14, v65
	v_mov_b32_e32 v15, v65
	v_mov_b32_e32 v16, 0
	v_mov_b32_e32 v17, v65
	v_mov_b32_e32 v18, v65
	v_mov_b32_e32 v19, v65
	v_mov_b32_e32 v20, 0
	v_mov_b32_e32 v21, v65
	v_mov_b32_e32 v22, v65
	v_mov_b32_e32 v23, v65
	v_mov_b32_e32 v24, 0
	v_mov_b32_e32 v25, v65
	v_mov_b32_e32 v26, v65
	v_mov_b32_e32 v27, v65
	v_mov_b32_e32 v28, 0
	v_mov_b32_e32 v29, v65
	v_mov_b32_e32 v30, v65
	v_mov_b32_e32 v31, v65
	v_mov_b32_e32 v32, 0
	v_mov_b32_e32 v33, v65
	v_mov_b32_e32 v34, v65
	v_mov_b32_e32 v35, v65
	v_mov_b32_e32 v36, 0
	v_mov_b32_e32 v37, v65
	v_mov_b32_e32 v38, v65
	v_mov_b32_e32 v39, v65
	v_mov_b32_e32 v40, 0
	v_mov_b32_e32 v41, v65
	v_mov_b32_e32 v42, v65
	v_mov_b32_e32 v43, v65
	v_mov_b32_e32 v44, 0
	v_mov_b32_e32 v45, v65
	v_mov_b32_e32 v46, v65
	v_mov_b32_e32 v47, v65
	v_mov_b32_e32 v48, 0
	v_mov_b32_e32 v49, v65
	v_mov_b32_e32 v50, v65
	v_mov_b32_e32 v51, v65
	v_mov_b32_e32 v52, 0
	v_mov_b32_e32 v53, v65
	v_mov_b32_e32 v54, v65
	v_mov_b32_e32 v55, v65
	v_mov_b32_e32 v56, 0
	v_mov_b32_e32 v57, v65
	v_mov_b32_e32 v58, v65
	v_mov_b32_e32 v59, v65
	v_mov_b32_e32 v60, 0
	v_mov_b32_e32 v61, v65
	v_mov_b32_e32 v62, v65
	v_mov_b32_e32 v63, v65
	s_branch .LBB0_610

.LBB0_882:
	s_mul_hi_u32 s98, s3, 0xba2e8ba3
	s_lshr_b32 s98, s98, 3
	s_mul_i32 s99, s98, 11
	s_sub_u32 s99, s3, s99
	s_and_b32 s100, s90, 1
	s_lshl_b32 s98, s98, 1
	s_or_b32 s98, s98, s100
	s_lshr_b32 s100, s90, 1
	s_lshl_b32 s99, s99, 2
	s_or_b32 s99, s99, s100
	s_and_b32 s101, s98, 7
	s_lshr_b32 s98, s98, 3
	s_mul_i32 s99, s99, 17
	s_add_u32 s98, s98, s99
	s_lshl_b32 s99, s98, 3
	s_or_b32 s99, s99, s101
	s_mul_hi_i32 s10, s98, 0x78787879
	s_lshr_b32 s11, s10, 31
	s_ashr_i32 s10, s10, 3
	s_add_i32 s10, s10, s11
	s_mul_i32 s11, s10, 0xffffffef
	s_add_i32 s11, s11, s98
	s_lshl_b32 s11, s11, 3
	s_or_b32 s12, s11, s101
	v_mov_b32_e32 v0, v174
	s_ashr_i32 s13, s12, 31
	s_lshl_b64 s[34:35], s[12:13], 18
	v_bfe_u32 v2, v0, 1, 3
	v_lshrrev_b32_e32 v3, 4, v0
	v_bfe_u32 v4, v0, 4, 2
	v_lshlrev_b32_e32 v5, 7, v0
	v_and_b32_e32 v6, 0x780, v5
	v_bitop3_b32 v3, v3, v2, 3 bitop3:0x6c
	v_bitop3_b32 v2, v4, v2, 4 bitop3:0x36
	s_add_u32 s34, s38, s34
	v_lshl_or_b32 v7, v3, 4, v6
	v_lshl_or_b32 v6, v2, 4, v6
	v_lshlrev_b32_e32 v2, 6, v0
	s_addc_u32 s35, s39, s35
	s_ashr_i32 s11, s10, 31
	v_lshlrev_b32_e32 v1, 8, v0
	v_and_b32_e32 v8, 0xffffe000, v2
	v_lshlrev_b32_e32 v2, 4, v0
	s_lshl_b64 s[84:85], s[10:11], 18
	v_and_b32_e32 v1, 0xfffff800, v1
	v_xor_b32_e32 v0, v2, v0
	s_movk_i32 s11, 0x70
	v_add_u32_e32 v100, 0, v2
	v_and_or_b32 v64, v0, s11, v1
	v_readfirstlane_b32 s11, v100
	v_add_u32_e32 v101, 0x1000, v100
	s_mov_b32 m0, s11
	v_readfirstlane_b32 s11, v101
	v_add_u32_e32 v102, 0x2000, v100
	global_load_lds_dwordx4 v64, s[34:35]
	v_add_u32_e32 v0, 0x10000, v64
	s_mov_b32 m0, s11
	v_readfirstlane_b32 s11, v102
	v_add_u32_e32 v103, 0x3000, v100
	global_load_lds_dwordx4 v0, s[34:35]
	v_add_u32_e32 v2, 0x20000, v64
	s_mov_b32 m0, s11
	v_readfirstlane_b32 s11, v103
	v_add_u32_e32 v104, 0x4000, v100
	s_add_u32 s88, s92, s84
	global_load_lds_dwordx4 v2, s[34:35]
	v_add_u32_e32 v4, 0x30000, v64
	s_mov_b32 m0, s11
	v_readfirstlane_b32 s11, v104
	v_add_u32_e32 v105, 0x5000, v100
	s_addc_u32 s89, s93, s85
	global_load_lds_dwordx4 v4, s[34:35]
	s_mov_b32 m0, s11
	v_readfirstlane_b32 s11, v105
	v_add_u32_e32 v106, 0x6000, v100
	global_load_lds_dwordx4 v64, s[88:89]
	s_mov_b32 m0, s11
	v_readfirstlane_b32 s11, v106
	v_add_u32_e32 v107, 0x7000, v100
	global_load_lds_dwordx4 v0, s[88:89]
	s_mov_b32 m0, s11
	v_readfirstlane_b32 s11, v107
	global_load_lds_dwordx4 v2, s[88:89]
	s_mov_b32 m0, s11
	s_mul_i32 s11, s10, 0x88
	global_load_lds_dwordx4 v4, s[88:89]
	s_sub_i32 s34, s99, s11
	s_ashr_i32 s35, s34, 31
	s_lshl_b64 s[34:35], s[34:35], 18
	s_add_u32 s34, s38, s34
	v_and_b32_e32 v9, 0x2000, v5
	v_mov_b32_e32 v1, v65
	v_mov_b32_e32 v3, v65
	v_mov_b32_e32 v5, v65
	s_addc_u32 s35, s39, s35
	v_lshl_add_u64 v[66:67], s[34:35], 0, v[64:65]
	v_lshl_add_u64 v[68:69], s[34:35], 0, v[0:1]
	v_lshl_add_u64 v[70:71], s[34:35], 0, v[2:3]
	v_lshl_add_u64 v[72:73], s[34:35], 0, v[4:5]
	s_add_u32 s34, s36, s84
	v_add_u32_e32 v8, 0, v8
	v_add_u32_e32 v9, 0, v9
	s_addc_u32 s35, s37, s85
	v_lshl_add_u64 v[74:75], s[34:35], 0, v[64:65]
	v_lshl_add_u64 v[76:77], s[34:35], 0, v[0:1]
	v_lshl_add_u64 v[78:79], s[34:35], 0, v[2:3]
	v_lshl_add_u64 v[80:81], s[34:35], 0, v[4:5]
	s_mov_b64 s[84:85], 0
	v_add_u32_e32 v64, 0x8000, v100
	v_add_u32_e32 v108, 0x9000, v100
	v_add_u32_e32 v109, 0xa000, v100
	v_add_u32_e32 v110, 0xb000, v100
	v_add_u32_e32 v111, 0xc000, v100
	v_add_u32_e32 v112, 0xd000, v100
	v_add_u32_e32 v113, 0xe000, v100
	v_add_u32_e32 v114, 0xf000, v100
	v_add_u32_e32 v115, v8, v7
	v_add_u32_e32 v116, v9, v7
	v_add_u32_e32 v117, v8, v6
	v_add_u32_e32 v118, v9, v6
	s_mov_b32 s11, 0
	v_mov_b32_e32 v0, 0
	v_mov_b32_e32 v2, v65
	v_mov_b32_e32 v8, 0
	v_mov_b32_e32 v9, v65
	v_mov_b32_e32 v10, v65
	v_mov_b32_e32 v11, v65
	v_mov_b32_e32 v4, 0
	v_mov_b32_e32 v6, v65
	v_mov_b32_e32 v7, v65
	v_mov_b32_e32 v12, 0
	v_mov_b32_e32 v13, v65
	v_mov_b32_e32 v14, v65
	v_mov_b32_e32 v15, v65
	v_mov_b32_e32 v16, 0
	v_mov_b32_e32 v17, v65
	v_mov_b32_e32 v18, v65
	v_mov_b32_e32 v19, v65
	v_mov_b32_e32 v24, 0
	v_mov_b32_e32 v25, v65
	v_mov_b32_e32 v26, v65
	v_mov_b32_e32 v27, v65
	v_mov_b32_e32 v20, 0
	v_mov_b32_e32 v21, v65
	v_mov_b32_e32 v22, v65
	v_mov_b32_e32 v23, v65
	v_mov_b32_e32 v28, 0
	v_mov_b32_e32 v29, v65
	v_mov_b32_e32 v30, v65
	v_mov_b32_e32 v31, v65
	v_mov_b32_e32 v32, 0
	v_mov_b32_e32 v33, v65
	v_mov_b32_e32 v34, v65
	v_mov_b32_e32 v35, v65
	v_mov_b32_e32 v40, 0
	v_mov_b32_e32 v41, v65
	v_mov_b32_e32 v42, v65
	v_mov_b32_e32 v43, v65
	v_mov_b32_e32 v36, 0
	v_mov_b32_e32 v37, v65
	v_mov_b32_e32 v38, v65
	v_mov_b32_e32 v39, v65
	v_mov_b32_e32 v44, 0
	v_mov_b32_e32 v45, v65
	v_mov_b32_e32 v46, v65
	v_mov_b32_e32 v47, v65
	v_mov_b32_e32 v48, 0
	v_mov_b32_e32 v49, v65
	v_mov_b32_e32 v50, v65
	v_mov_b32_e32 v51, v65
	v_mov_b32_e32 v56, 0
	v_mov_b32_e32 v57, v65
	v_mov_b32_e32 v58, v65
	v_mov_b32_e32 v59, v65
	v_mov_b32_e32 v52, 0
	v_mov_b32_e32 v53, v65
	v_mov_b32_e32 v54, v65
	v_mov_b32_e32 v55, v65
	v_mov_b32_e32 v60, 0
	v_mov_b32_e32 v61, v65
	v_mov_b32_e32 v62, v65
	v_mov_b32_e32 v63, v65
	s_branch .LBB0_884

.LBB0_1591:
	s_lshr_b32 s98, s3, 3
	s_and_b32 s99, s3, 7
	s_and_b32 s100, s20, 1
	s_lshl_b32 s98, s98, 1
	s_or_b32 s98, s98, s100
	s_lshr_b32 s100, s20, 1
	s_lshl_b32 s99, s99, 2
	s_or_b32 s99, s99, s100
	s_and_b32 s101, s98, 7
	s_lshr_b32 s98, s98, 3
	s_mul_i32 s99, s99, 17
	s_add_u32 s98, s98, s99
	s_lshl_b32 s99, s98, 3
	s_or_b32 s99, s99, s101
	s_mul_hi_i32 s10, s98, 0x78787879
	s_lshr_b32 s11, s10, 31
	s_ashr_i32 s10, s10, 3
	s_add_i32 s10, s10, s11
	s_mul_i32 s11, s10, 0xffffffef
	s_add_i32 s11, s11, s98
	s_lshl_b32 s11, s11, 3
	v_mov_b32_e32 v0, v174
	s_or_b32 s12, s11, s101
	s_ashr_i32 s13, s12, 31
	v_bfe_u32 v2, v0, 1, 3
	v_lshrrev_b32_e32 v3, 4, v0
	v_bfe_u32 v4, v0, 4, 2
	v_lshlrev_b32_e32 v5, 7, v0
	v_and_b32_e32 v6, 0x780, v5
	v_bitop3_b32 v3, v3, v2, 3 bitop3:0x6c
	v_bitop3_b32 v2, v4, v2, 4 bitop3:0x36
	s_lshl_b64 s[16:17], s[12:13], 18
	v_lshl_or_b32 v7, v3, 4, v6
	v_lshl_or_b32 v6, v2, 4, v6
	v_lshlrev_b32_e32 v2, 6, v0
	s_add_u32 s16, s38, s16
	v_and_b32_e32 v8, 0xffffe000, v2
	v_lshlrev_b32_e32 v2, 4, v0
	s_addc_u32 s17, s39, s17
	s_ashr_i32 s11, s10, 31
	v_lshlrev_b32_e32 v1, 8, v0
	v_add_u32_e32 v100, 0, v2
	s_lshl_b64 s[18:19], s[10:11], 18
	v_and_b32_e32 v1, 0xfffff800, v1
	v_xor_b32_e32 v0, v2, v0
	v_readfirstlane_b32 s11, v100
	v_add_u32_e32 v101, 0x1000, v100
	v_and_or_b32 v64, v0, s27, v1
	s_mov_b32 m0, s11
	v_readfirstlane_b32 s11, v101
	v_add_u32_e32 v102, 0x2000, v100
	global_load_lds_dwordx4 v64, s[16:17]
	v_add_u32_e32 v0, 0x10000, v64
	s_mov_b32 m0, s11
	v_readfirstlane_b32 s11, v102
	v_add_u32_e32 v103, 0x3000, v100
	global_load_lds_dwordx4 v0, s[16:17]
	v_add_u32_e32 v2, 0x20000, v64
	s_mov_b32 m0, s11
	v_readfirstlane_b32 s11, v103
	v_add_u32_e32 v104, 0x4000, v100
	s_add_u32 s34, s24, s18
	global_load_lds_dwordx4 v2, s[16:17]
	v_add_u32_e32 v4, 0x30000, v64
	s_mov_b32 m0, s11
	v_readfirstlane_b32 s11, v104
	v_add_u32_e32 v105, 0x5000, v100
	s_addc_u32 s35, s25, s19
	global_load_lds_dwordx4 v4, s[16:17]
	s_mov_b32 m0, s11
	v_readfirstlane_b32 s11, v105
	v_add_u32_e32 v106, 0x6000, v100
	global_load_lds_dwordx4 v64, s[34:35]
	s_mov_b32 m0, s11
	v_readfirstlane_b32 s11, v106
	v_add_u32_e32 v107, 0x7000, v100
	global_load_lds_dwordx4 v0, s[34:35]
	s_mov_b32 m0, s11
	v_readfirstlane_b32 s11, v107
	global_load_lds_dwordx4 v2, s[34:35]
	s_mov_b32 m0, s11
	s_mul_i32 s11, s10, 0x88
	global_load_lds_dwordx4 v4, s[34:35]
	s_sub_i32 s16, s99, s11
	s_ashr_i32 s17, s16, 31
	s_lshl_b64 s[16:17], s[16:17], 18
	s_add_u32 s16, s38, s16
	v_and_b32_e32 v9, 0x2000, v5
	v_mov_b32_e32 v1, v65
	v_mov_b32_e32 v3, v65
	v_mov_b32_e32 v5, v65
	s_addc_u32 s17, s39, s17
	v_lshl_add_u64 v[66:67], s[16:17], 0, v[64:65]
	v_lshl_add_u64 v[68:69], s[16:17], 0, v[0:1]
	v_lshl_add_u64 v[70:71], s[16:17], 0, v[2:3]
	v_lshl_add_u64 v[72:73], s[16:17], 0, v[4:5]
	s_add_u32 s16, s36, s18
	v_add_u32_e32 v8, 0, v8
	v_add_u32_e32 v9, 0, v9
	s_addc_u32 s17, s37, s19
	v_lshl_add_u64 v[74:75], s[16:17], 0, v[64:65]
	v_lshl_add_u64 v[76:77], s[16:17], 0, v[0:1]
	v_lshl_add_u64 v[78:79], s[16:17], 0, v[2:3]
	v_lshl_add_u64 v[80:81], s[16:17], 0, v[4:5]
	s_mov_b64 s[16:17], 0
	v_add_u32_e32 v64, 0x8000, v100
	v_add_u32_e32 v108, 0x9000, v100
	v_add_u32_e32 v109, 0xa000, v100
	v_add_u32_e32 v110, 0xb000, v100
	v_add_u32_e32 v111, 0xc000, v100
	v_add_u32_e32 v112, 0xd000, v100
	v_add_u32_e32 v113, 0xe000, v100
	v_add_u32_e32 v114, 0xf000, v100
	v_add_u32_e32 v115, v8, v7
	v_add_u32_e32 v116, v9, v7
	v_add_u32_e32 v117, v8, v6
	v_add_u32_e32 v118, v9, v6
	s_mov_b32 s11, 0
	v_mov_b32_e32 v0, 0
	v_mov_b32_e32 v2, v65
	v_mov_b32_e32 v4, 0
	v_mov_b32_e32 v6, v65
	v_mov_b32_e32 v7, v65
	v_mov_b32_e32 v8, 0
	v_mov_b32_e32 v9, v65
	v_mov_b32_e32 v10, v65
	v_mov_b32_e32 v11, v65
	v_mov_b32_e32 v12, 0
	v_mov_b32_e32 v13, v65
	v_mov_b32_e32 v14, v65
	v_mov_b32_e32 v15, v65
	v_mov_b32_e32 v16, 0
	v_mov_b32_e32 v17, v65
	v_mov_b32_e32 v18, v65
	v_mov_b32_e32 v19, v65
	v_mov_b32_e32 v20, 0
	v_mov_b32_e32 v21, v65
	v_mov_b32_e32 v22, v65
	v_mov_b32_e32 v23, v65
	v_mov_b32_e32 v24, 0
	v_mov_b32_e32 v25, v65
	v_mov_b32_e32 v26, v65
	v_mov_b32_e32 v27, v65
	v_mov_b32_e32 v28, 0
	v_mov_b32_e32 v29, v65
	v_mov_b32_e32 v30, v65
	v_mov_b32_e32 v31, v65
	v_mov_b32_e32 v32, 0
	v_mov_b32_e32 v33, v65
	v_mov_b32_e32 v34, v65
	v_mov_b32_e32 v35, v65
	v_mov_b32_e32 v36, 0
	v_mov_b32_e32 v37, v65
	v_mov_b32_e32 v38, v65
	v_mov_b32_e32 v39, v65
	v_mov_b32_e32 v40, 0
	v_mov_b32_e32 v41, v65
	v_mov_b32_e32 v42, v65
	v_mov_b32_e32 v43, v65
	v_mov_b32_e32 v44, 0
	v_mov_b32_e32 v45, v65
	v_mov_b32_e32 v46, v65
	v_mov_b32_e32 v47, v65
	v_mov_b32_e32 v48, 0
	v_mov_b32_e32 v49, v65
	v_mov_b32_e32 v50, v65
	v_mov_b32_e32 v51, v65
	v_mov_b32_e32 v52, 0
	v_mov_b32_e32 v53, v65
	v_mov_b32_e32 v54, v65
	v_mov_b32_e32 v55, v65
	v_mov_b32_e32 v56, 0
	v_mov_b32_e32 v57, v65
	v_mov_b32_e32 v58, v65
	v_mov_b32_e32 v59, v65
	v_mov_b32_e32 v60, 0
	v_mov_b32_e32 v61, v65
	v_mov_b32_e32 v62, v65
	v_mov_b32_e32 v63, v65
	s_branch .LBB0_1593

.LBB0_1865:
	s_mul_hi_u32 s98, s3, 0xba2e8ba3
	s_lshr_b32 s98, s98, 3
	s_mul_i32 s99, s98, 11
	s_sub_u32 s99, s3, s99
	s_and_b32 s100, s20, 1
	s_lshl_b32 s98, s98, 1
	s_or_b32 s98, s98, s100
	s_lshr_b32 s100, s20, 1
	s_lshl_b32 s99, s99, 2
	s_or_b32 s99, s99, s100
	s_and_b32 s101, s98, 7
	s_lshr_b32 s98, s98, 3
	s_mul_i32 s99, s99, 17
	s_add_u32 s98, s98, s99
	s_lshl_b32 s99, s98, 3
	s_or_b32 s99, s99, s101
	s_mul_hi_i32 s10, s98, 0x78787879
	s_lshr_b32 s11, s10, 31
	s_ashr_i32 s10, s10, 3
	s_add_i32 s10, s10, s11
	s_mul_i32 s11, s10, 0xffffffef
	s_add_i32 s11, s11, s98
	s_lshl_b32 s11, s11, 3
	v_mov_b32_e32 v0, v174
	s_or_b32 s12, s11, s101
	s_ashr_i32 s13, s12, 31
	v_bfe_u32 v2, v0, 1, 3
	v_lshrrev_b32_e32 v3, 4, v0
	v_bfe_u32 v4, v0, 4, 2
	v_lshlrev_b32_e32 v5, 7, v0
	v_and_b32_e32 v6, 0x780, v5
	v_bitop3_b32 v3, v3, v2, 3 bitop3:0x6c
	v_bitop3_b32 v2, v4, v2, 4 bitop3:0x36
	s_lshl_b64 s[16:17], s[12:13], 18
	v_lshl_or_b32 v7, v3, 4, v6
	v_lshl_or_b32 v6, v2, 4, v6
	v_lshlrev_b32_e32 v2, 6, v0
	s_add_u32 s16, s38, s16
	v_and_b32_e32 v8, 0xffffe000, v2
	v_lshlrev_b32_e32 v2, 4, v0
	s_addc_u32 s17, s39, s17
	s_ashr_i32 s11, s10, 31
	v_lshlrev_b32_e32 v1, 8, v0
	v_add_u32_e32 v100, 0, v2
	s_lshl_b64 s[18:19], s[10:11], 18
	v_and_b32_e32 v1, 0xfffff800, v1
	v_xor_b32_e32 v0, v2, v0
	v_readfirstlane_b32 s11, v100
	v_add_u32_e32 v101, 0x1000, v100
	v_and_or_b32 v64, v0, s25, v1
	s_mov_b32 m0, s11
	v_readfirstlane_b32 s11, v101
	v_add_u32_e32 v102, 0x2000, v100
	global_load_lds_dwordx4 v64, s[16:17]
	v_add_u32_e32 v0, 0x10000, v64
	s_mov_b32 m0, s11
	v_readfirstlane_b32 s11, v102
	v_add_u32_e32 v103, 0x3000, v100
	global_load_lds_dwordx4 v0, s[16:17]
	v_add_u32_e32 v2, 0x20000, v64
	s_mov_b32 m0, s11
	v_readfirstlane_b32 s11, v103
	v_add_u32_e32 v104, 0x4000, v100
	s_add_u32 s34, s22, s18
	global_load_lds_dwordx4 v2, s[16:17]
	v_add_u32_e32 v4, 0x30000, v64
	s_mov_b32 m0, s11
	v_readfirstlane_b32 s11, v104
	v_add_u32_e32 v105, 0x5000, v100
	s_addc_u32 s35, s23, s19
	global_load_lds_dwordx4 v4, s[16:17]
	s_mov_b32 m0, s11
	v_readfirstlane_b32 s11, v105
	v_add_u32_e32 v106, 0x6000, v100
	global_load_lds_dwordx4 v64, s[34:35]
	s_mov_b32 m0, s11
	v_readfirstlane_b32 s11, v106
	v_add_u32_e32 v107, 0x7000, v100
	global_load_lds_dwordx4 v0, s[34:35]
	s_mov_b32 m0, s11
	v_readfirstlane_b32 s11, v107
	global_load_lds_dwordx4 v2, s[34:35]
	s_mov_b32 m0, s11
	s_mul_i32 s11, s10, 0x88
	global_load_lds_dwordx4 v4, s[34:35]
	s_sub_i32 s16, s99, s11
	s_ashr_i32 s17, s16, 31
	s_lshl_b64 s[16:17], s[16:17], 18
	s_add_u32 s16, s38, s16
	v_and_b32_e32 v9, 0x2000, v5
	v_mov_b32_e32 v1, v65
	v_mov_b32_e32 v3, v65
	v_mov_b32_e32 v5, v65
	s_addc_u32 s17, s39, s17
	v_lshl_add_u64 v[66:67], s[16:17], 0, v[64:65]
	v_lshl_add_u64 v[68:69], s[16:17], 0, v[0:1]
	v_lshl_add_u64 v[70:71], s[16:17], 0, v[2:3]
	v_lshl_add_u64 v[72:73], s[16:17], 0, v[4:5]
	s_add_u32 s16, s36, s18
	v_add_u32_e32 v8, 0, v8
	v_add_u32_e32 v9, 0, v9
	s_addc_u32 s17, s37, s19
	v_lshl_add_u64 v[74:75], s[16:17], 0, v[64:65]
	v_lshl_add_u64 v[76:77], s[16:17], 0, v[0:1]
	v_lshl_add_u64 v[78:79], s[16:17], 0, v[2:3]
	v_lshl_add_u64 v[80:81], s[16:17], 0, v[4:5]
	s_mov_b64 s[16:17], 0
	v_add_u32_e32 v64, 0x8000, v100
	v_add_u32_e32 v108, 0x9000, v100
	v_add_u32_e32 v109, 0xa000, v100
	v_add_u32_e32 v110, 0xb000, v100
	v_add_u32_e32 v111, 0xc000, v100
	v_add_u32_e32 v112, 0xd000, v100
	v_add_u32_e32 v113, 0xe000, v100
	v_add_u32_e32 v114, 0xf000, v100
	v_add_u32_e32 v115, v8, v7
	v_add_u32_e32 v116, v9, v7
	v_add_u32_e32 v117, v8, v6
	v_add_u32_e32 v118, v9, v6
	s_mov_b32 s11, 0
	v_mov_b32_e32 v0, 0
	v_mov_b32_e32 v2, v65
	v_mov_b32_e32 v8, 0
	v_mov_b32_e32 v9, v65
	v_mov_b32_e32 v10, v65
	v_mov_b32_e32 v11, v65
	v_mov_b32_e32 v4, 0
	v_mov_b32_e32 v6, v65
	v_mov_b32_e32 v7, v65
	v_mov_b32_e32 v12, 0
	v_mov_b32_e32 v13, v65
	v_mov_b32_e32 v14, v65
	v_mov_b32_e32 v15, v65
	v_mov_b32_e32 v16, 0
	v_mov_b32_e32 v17, v65
	v_mov_b32_e32 v18, v65
	v_mov_b32_e32 v19, v65
	v_mov_b32_e32 v24, 0
	v_mov_b32_e32 v25, v65
	v_mov_b32_e32 v26, v65
	v_mov_b32_e32 v27, v65
	v_mov_b32_e32 v20, 0
	v_mov_b32_e32 v21, v65
	v_mov_b32_e32 v22, v65
	v_mov_b32_e32 v23, v65
	v_mov_b32_e32 v28, 0
	v_mov_b32_e32 v29, v65
	v_mov_b32_e32 v30, v65
	v_mov_b32_e32 v31, v65
	v_mov_b32_e32 v32, 0
	v_mov_b32_e32 v33, v65
	v_mov_b32_e32 v34, v65
	v_mov_b32_e32 v35, v65
	v_mov_b32_e32 v40, 0
	v_mov_b32_e32 v41, v65
	v_mov_b32_e32 v42, v65
	v_mov_b32_e32 v43, v65
	v_mov_b32_e32 v36, 0
	v_mov_b32_e32 v37, v65
	v_mov_b32_e32 v38, v65
	v_mov_b32_e32 v39, v65
	v_mov_b32_e32 v44, 0
	v_mov_b32_e32 v45, v65
	v_mov_b32_e32 v46, v65
	v_mov_b32_e32 v47, v65
	v_mov_b32_e32 v48, 0
	v_mov_b32_e32 v49, v65
	v_mov_b32_e32 v50, v65
	v_mov_b32_e32 v51, v65
	v_mov_b32_e32 v56, 0
	v_mov_b32_e32 v57, v65
	v_mov_b32_e32 v58, v65
	v_mov_b32_e32 v59, v65
	v_mov_b32_e32 v52, 0
	v_mov_b32_e32 v53, v65
	v_mov_b32_e32 v54, v65
	v_mov_b32_e32 v55, v65
	v_mov_b32_e32 v60, 0
	v_mov_b32_e32 v61, v65
	v_mov_b32_e32 v62, v65
	v_mov_b32_e32 v63, v65
	s_branch .LBB0_1867
